# GDN chain section F: 16 packed v_pk_mul_f32 on the state accumulators (feeding MFMA C operands) split into scalar v_mul_f32 pairs
# baseline (speedup 1.0000x reference)
; #define LAS __attribute__((address_space(3)))
; __device__ __forceinline__ unsigned pk2(float lo, float hi) { const f32v2_t f = {lo, hi}; const bf16v2_t b = __builtin_convertvector(f, bf16v2_t); return __builtin_bit_cast(unsigned, b); }
; #define WAVE_SYNC() do { asm volatile("s_waitcnt lgkmcnt(0)" ::: "memory"); __builtin_amdgcn_wave_barrier(); asm volatile("" ::: "memory"); } while (0)
; #define MFMA16(a, b, c) __builtin_amdgcn_mfma_f32_16x16x32_bf16((a), (b), (c), 0, 0, 0)
; template <int MODE>
; __device__ NOINL void chain_item(const LAS Params* lp, int l, int item, bool ctx_out, LAS unsigned char* lds) {
;     ...
;         for (int dk = 0; dk < NDK; ++dk) { u32x2 pk; pk.x = pk2(Sacc[dk][0], Sacc[dk][1]); pk.y = pk2(Sacc[dk][2], Sacc[dk][3]); *(LAS u32x2*)(ST + fr * 136 + 16 * dk + 4 * fq) = pk; }
;         WAVE_SYNC();
;         f32x4 qs[4], ksm[4];
; #pragma unroll
;         for (int ct = 0; ct < 4; ++ct) { qs[ct] = (f32x4){0.f, 0.f, 0.f, 0.f}; ksm[ct] = (f32x4){0.f, 0.f, 0.f, 0.f}; }
; #pragma unroll
;         for (int ks = 0; ks < NKS; ++ks) {
;             const bf16x8 Bf = *(const LAS bf16x8*)(ST + fr * 136 + ks * 32 + fq * 8);
; #pragma unroll
;             for (int ct = 0; ct < 4; ++ct) {
;                 const bf16x8 Aq = *(const LAS bf16x8*)(Qs + (16 * ct + fr) * 136 + kcol + ks * 32 + fq * 8);
;                 qs[ct] = MFMA16(Aq, Bf, qs[ct]);
;                 if (MODE == 0) { const bf16x8 Ak = *(const LAS bf16x8*)(Ks + (16 * ct + fr) * 136 + ks * 32 + fq * 8); ksm[ct] = MFMA16(Ak, Bf, ksm[ct]); }
;             }
;         }
.LBB0_1141:
	s_or_b64 exec, exec, s[62:63]
	ds_write_b16 v178, v68
	v_cvt_pk_bf16_f32 v68, v28, v29
	v_cvt_pk_bf16_f32 v69, v30, v31
	v_cvt_pk_bf16_f32 v70, v40, v41
	v_cvt_pk_bf16_f32 v71, v42, v43
	ds_write2_b64 v113, v[68:69], v[70:71] offset1:4
	v_cvt_pk_bf16_f32 v68, v32, v33
	v_cvt_pk_bf16_f32 v69, v34, v35
	v_cvt_pk_bf16_f32 v70, v36, v37
	v_cvt_pk_bf16_f32 v71, v38, v39
	ds_write2_b64 v113, v[68:69], v[70:71] offset0:8 offset1:12
	v_cvt_pk_bf16_f32 v68, v56, v57
	v_cvt_pk_bf16_f32 v69, v58, v59
	v_cvt_pk_bf16_f32 v70, v52, v53
	v_cvt_pk_bf16_f32 v71, v54, v55
	ds_write2_b64 v113, v[68:69], v[70:71] offset0:16 offset1:20
	v_cvt_pk_bf16_f32 v68, v44, v45
	v_cvt_pk_bf16_f32 v69, v46, v47
	v_cvt_pk_bf16_f32 v70, v48, v49
	v_cvt_pk_bf16_f32 v71, v50, v51
	ds_write2_b64 v113, v[68:69], v[70:71] offset0:24 offset1:28
	s_waitcnt lgkmcnt(0)
	v_add_u32_e32 v119, v113, v154
	ds_read_b128 v[84:87], v119
	ds_read_b128 v[100:103], v179
	ds_read_b128 v[104:107], v179 offset:17408
	ds_read_b128 v[194:197], v179 offset:4352
	ds_read_b128 v[236:239], v179 offset:21760
	ds_read_b128 v[240:243], v179 offset:8704
	ds_read_b128 v[244:247], v179 offset:26112
	ds_read_b128 v[248:251], v179 offset:13056
	v_add_u32_e32 v121, 0x25500, v110
	s_waitcnt lgkmcnt(6)
	v_mfma_f32_16x16x32_bf16 v[96:99], v[100:103], v[84:87], 0
	ds_read_b128 v[100:103], v179 offset:30464
	ds_read_b128 v[88:91], v119 offset:64
	s_add_i32 s5, s4, 4
	s_waitcnt lgkmcnt(7)
	v_mfma_f32_16x16x32_bf16 v[198:201], v[104:107], v[84:87], 0
	ds_read_b128 v[104:107], v179 offset:64
	s_and_b64 s[20:21], vcc, exec
	s_waitcnt lgkmcnt(7)
	v_mfma_f32_16x16x32_bf16 v[92:95], v[194:197], v[84:87], 0
	ds_read_b128 v[194:197], v179 offset:17472
	s_cselect_b32 s5, s1, s5
	s_waitcnt lgkmcnt(7)
	v_mfma_f32_16x16x32_bf16 v[232:235], v[236:239], v[84:87], 0
	ds_read_b128 v[236:239], v179 offset:4416
	s_add_i32 s22, s4, 40
	s_waitcnt lgkmcnt(7)
	v_mfma_f32_16x16x32_bf16 v[80:83], v[240:243], v[84:87], 0
	ds_read_b128 v[240:243], v179 offset:21824
	s_and_b64 s[20:21], vcc, exec
	s_waitcnt lgkmcnt(7)
	v_mfma_f32_16x16x32_bf16 v[72:75], v[244:247], v[84:87], 0
	ds_read_b128 v[244:247], v179 offset:8768
	s_cselect_b32 s20, s1, s22
	s_waitcnt lgkmcnt(7)
	v_mfma_f32_16x16x32_bf16 v[76:79], v[248:251], v[84:87], 0
	ds_read_b128 v[248:251], v179 offset:26176
	s_cmp_lt_u32 s1, 4
	s_waitcnt lgkmcnt(7)
	v_mfma_f32_16x16x32_bf16 v[68:71], v[100:103], v[84:87], 0
	ds_read_b128 v[100:103], v179 offset:13120
	s_cselect_b32 s1, s5, s20
	s_waitcnt lgkmcnt(6)
	v_mfma_f32_16x16x32_bf16 v[96:99], v[104:107], v[88:91], v[96:99]
	ds_read_b128 v[104:107], v179 offset:30528
	ds_read_b128 v[84:87], v119 offset:128
	s_lshl_b32 s5, s1, 6
	s_waitcnt lgkmcnt(7)
	v_mfma_f32_16x16x32_bf16 v[198:201], v[194:197], v[88:91], v[198:201]
	ds_read_b128 v[194:197], v179 offset:128
	s_add_i32 s20, s18, s5
	s_waitcnt lgkmcnt(7)
	v_mfma_f32_16x16x32_bf16 v[92:95], v[236:239], v[88:91], v[92:95]
	ds_read_b128 v[236:239], v179 offset:17536
	s_or_b32 s5, s5, s38
	s_waitcnt lgkmcnt(7)
	v_mfma_f32_16x16x32_bf16 v[232:235], v[240:243], v[88:91], v[232:235]
	ds_read_b128 v[240:243], v179 offset:4480
	s_cmp_lt_u32 s1, 4
	s_waitcnt lgkmcnt(7)
	v_mfma_f32_16x16x32_bf16 v[80:83], v[244:247], v[88:91], v[80:83]
	ds_read_b128 v[244:247], v179 offset:21888
	s_cselect_b32 s1, s5, s20
	s_waitcnt lgkmcnt(7)
	v_mfma_f32_16x16x32_bf16 v[72:75], v[248:251], v[88:91], v[72:75]
	ds_read_b128 v[248:251], v179 offset:8832
	s_mul_hi_i32 s21, s1, s19
	s_waitcnt lgkmcnt(7)
	v_mfma_f32_16x16x32_bf16 v[76:79], v[100:103], v[88:91], v[76:79]
	ds_read_b128 v[100:103], v179 offset:26240
	s_mul_i32 s20, s1, s19
	s_waitcnt lgkmcnt(7)
	v_mfma_f32_16x16x32_bf16 v[68:71], v[104:107], v[88:91], v[68:71]
	ds_read_b128 v[104:107], v179 offset:13184
	v_mov_b32_e32 v123, v1
	s_waitcnt lgkmcnt(6)
	v_mfma_f32_16x16x32_bf16 v[96:99], v[194:197], v[84:87], v[96:99]
	ds_read_b128 v[194:197], v179 offset:30592
	ds_read_b128 v[88:91], v119 offset:192
	v_add_u32_e32 v119, s34, v155
	v_mov_b32_e32 v125, v1
	s_waitcnt lgkmcnt(7)
	v_mfma_f32_16x16x32_bf16 v[198:201], v[236:239], v[84:87], v[198:201]
	ds_read_b128 v[236:239], v179 offset:192
	v_mov_b32_e32 v127, v1
	s_waitcnt lgkmcnt(7)
	v_mfma_f32_16x16x32_bf16 v[92:95], v[240:243], v[84:87], v[92:95]
	ds_read_b128 v[240:243], v179 offset:17600
	v_mov_b32_e32 v129, v1
	s_waitcnt lgkmcnt(7)
	v_mfma_f32_16x16x32_bf16 v[232:235], v[244:247], v[84:87], v[232:235]
	ds_read_b128 v[244:247], v179 offset:4544
	v_mov_b32_e32 v131, v1
	s_waitcnt lgkmcnt(7)
	v_mfma_f32_16x16x32_bf16 v[80:83], v[248:251], v[84:87], v[80:83]
	ds_read_b128 v[248:251], v179 offset:21952
	v_mov_b32_e32 v133, v1
	s_waitcnt lgkmcnt(7)
	v_mfma_f32_16x16x32_bf16 v[72:75], v[100:103], v[84:87], v[72:75]
	ds_read_b128 v[100:103], v179 offset:8896
	v_mov_b32_e32 v135, v1
	s_waitcnt lgkmcnt(7)
	v_mfma_f32_16x16x32_bf16 v[76:79], v[104:107], v[84:87], v[76:79]
	ds_read_b128 v[104:107], v179 offset:26304
	v_mov_b32_e32 v137, v1
	s_waitcnt lgkmcnt(7)
	v_mfma_f32_16x16x32_bf16 v[68:71], v[194:197], v[84:87], v[68:71]
	ds_read_b128 v[194:197], v179 offset:13248
	v_mov_b32_e32 v139, v1
	s_waitcnt lgkmcnt(6)
	v_mfma_f32_16x16x32_bf16 v[96:99], v[236:239], v[88:91], v[96:99]
	ds_read_b128 v[236:239], v179 offset:30656
	v_mov_b32_e32 v141, v1
	s_waitcnt lgkmcnt(6)
	v_mfma_f32_16x16x32_bf16 v[198:201], v[240:243], v[88:91], v[198:201]
	v_mov_b32_e32 v143, v1
	s_waitcnt lgkmcnt(5)
	v_mfma_f32_16x16x32_bf16 v[92:95], v[244:247], v[88:91], v[92:95]
	v_mov_b32_e32 v145, v1
	s_waitcnt lgkmcnt(4)
	v_mfma_f32_16x16x32_bf16 v[232:235], v[248:251], v[88:91], v[232:235]
	v_mov_b32_e32 v147, v1
	s_waitcnt lgkmcnt(3)
; #define LAS __attribute__((address_space(3)))
; __device__ __forceinline__ unsigned pk2(float lo, float hi) { const f32v2_t f = {lo, hi}; const bf16v2_t b = __builtin_convertvector(f, bf16v2_t); return __builtin_bit_cast(unsigned, b); }
; __device__ __forceinline__ float bflo(unsigned u) { return __uint_as_float(u << 16); }
; __device__ __forceinline__ float bfhi(unsigned u) { return __uint_as_float(u & 0xFFFF0000u); }
; template <int MODE>
; __device__ NOINL void chain_item(const LAS Params* lp, int l, int item, bool ctx_out, LAS unsigned char* lds) {
;     ...
;         float eg[4][4];
; #pragma unroll
;         for (int ct = 0; ct < 4; ++ct)
; #pragma unroll
;             for (int j = 0; j < 4; ++j) { const int c = 16 * ct + 4 * fq + j; eg[ct][j] = MODE == 0 ? gcs[128 + c] : __expf((float)(c + 1) * lg); }
;         bf16x8 Bv[2];
;         if (MODE == 0) {
; #pragma unroll
;             for (int ct = 0; ct < 4; ++ct) {
;                 const u32x2 vv = *(const LAS u32x2*)(VT + (dvrow + fr) * 72 + (((2 * ct + (fq >> 1)) ^ vkey) << 3) + 4 * (fq & 1));
;                 const float v4[4] = {bflo(vv.x), bfhi(vv.x), bflo(vv.y), bfhi(vv.y)};
;                 float r[4];
; #pragma unroll
;                 for (int j = 0; j < 4; ++j) r[j] = bts[16 * ct + 4 * fq + j] * (v4[j] - eg[ct][j] * ksm[ct][j]);
;                 u32x2 pk; pk.x = pk2(r[0], r[1]); pk.y = pk2(r[2], r[3]);
;                 *(LAS u32x2*)(RP + fr * 72 + 16 * ct + 4 * fq) = pk;
;             }
;             WAVE_SYNC();
;             bf16x8 Br[2];
;             Br[0] = *(const LAS bf16x8*)(RP + fr * 72 + fq * 8); Br[1] = *(const LAS bf16x8*)(RP + fr * 72 + 32 + fq * 8);
;             f32x4 vn[4];
; #pragma unroll
;             for (int ct = 0; ct < 4; ++ct) {
;                 vn[ct] = (f32x4){0.f, 0.f, 0.f, 0.f};
; #pragma unroll
;                 for (int ks = 0; ks < 2; ++ks) { const bf16x8 A = *(const LAS bf16x8*)(TT + (16 * ct + fr) * 72 + ks * 32 + fq * 8); vn[ct] = MFMA16(A, Br[ks], vn[ct]); }
;             }
;             WAVE_SYNC();
; #pragma unroll
;             for (int ct = 0; ct < 4; ++ct) { u32x2 pk; pk.x = pk2(vn[ct][0], vn[ct][1]); pk.y = pk2(vn[ct][2], vn[ct][3]); *(LAS u32x2*)(RP + fr * 72 + 16 * ct + 4 * fq) = pk; }
;             WAVE_SYNC();
;             Bv[0] = *(const LAS bf16x8*)(RP + fr * 72 + fq * 8); Bv[1] = *(const LAS bf16x8*)(RP + fr * 72 + 32 + fq * 8);
	v_mfma_f32_16x16x32_bf16 v[80:83], v[100:103], v[88:91], v[80:83]
	s_add_i32 s4, s4, -1
	s_waitcnt lgkmcnt(2)
	v_mfma_f32_16x16x32_bf16 v[72:75], v[104:107], v[88:91], v[72:75]
	s_cmp_lg_u32 s0, 36
	s_waitcnt lgkmcnt(1)
	v_mfma_f32_16x16x32_bf16 v[76:79], v[194:197], v[88:91], v[76:79]
	s_mov_b32 s1, s0
	s_waitcnt lgkmcnt(0)
	v_mfma_f32_16x16x32_bf16 v[68:71], v[236:239], v[88:91], v[68:71]
	ds_read_b64 v[88:89], v186 offset:53248
	ds_read_b128 v[104:107], v119 offset:512
	ds_read_b128 v[84:87], v121
	s_waitcnt lgkmcnt(2)
	v_lshlrev_b32_e32 v90, 16, v88
	v_and_b32_e32 v91, 0xffff0000, v88
	v_lshlrev_b32_e32 v88, 16, v89
	v_and_b32_e32 v89, 0xffff0000, v89
	s_waitcnt lgkmcnt(1)
	v_pk_fma_f32 v[90:91], v[198:199], v[104:105], v[90:91] neg_lo:[1,0,0] neg_hi:[1,0,0]
	v_pk_fma_f32 v[88:89], v[200:201], v[106:107], v[88:89] neg_lo:[1,0,0] neg_hi:[1,0,0]
	s_waitcnt lgkmcnt(0)
	v_pk_mul_f32 v[84:85], v[84:85], v[90:91]
	v_pk_mul_f32 v[86:87], v[86:87], v[88:89]
	v_cvt_pk_bf16_f32 v148, v84, v85
	v_cvt_pk_bf16_f32 v149, v86, v87
	ds_read_b128 v[100:103], v119 offset:576
	ds_read_b128 v[88:91], v119 offset:640
	ds_read_b128 v[84:87], v119 offset:704
	ds_write_b64 v158, v[148:149] offset:4352
	ds_read_b64 v[148:149], v187 offset:53248
	ds_read_b128 v[194:197], v121 offset:64
	v_add_u32_e32 v119, v158, v154
	s_waitcnt lgkmcnt(1)
	v_lshlrev_b32_e32 v198, 16, v148
	v_and_b32_e32 v199, 0xffff0000, v148
	v_lshlrev_b32_e32 v148, 16, v149
	v_and_b32_e32 v149, 0xffff0000, v149
	v_pk_fma_f32 v[198:199], v[232:233], v[100:101], v[198:199] neg_lo:[1,0,0] neg_hi:[1,0,0]
	v_pk_fma_f32 v[148:149], v[234:235], v[102:103], v[148:149] neg_lo:[1,0,0] neg_hi:[1,0,0]
	s_waitcnt lgkmcnt(0)
	v_pk_mul_f32 v[194:195], v[194:195], v[198:199]
	v_pk_mul_f32 v[148:149], v[196:197], v[148:149]
	v_cvt_pk_bf16_f32 v194, v194, v195
	v_cvt_pk_bf16_f32 v195, v148, v149
	ds_write_b64 v158, v[194:195] offset:4384
	ds_read_b64 v[148:149], v188 offset:53248
	ds_read_b128 v[194:197], v121 offset:128
	s_waitcnt lgkmcnt(1)
	v_lshlrev_b32_e32 v198, 16, v148
	v_and_b32_e32 v199, 0xffff0000, v148
	v_lshlrev_b32_e32 v148, 16, v149
	v_and_b32_e32 v149, 0xffff0000, v149
	v_pk_fma_f32 v[72:73], v[72:73], v[88:89], v[198:199] neg_lo:[1,0,0] neg_hi:[1,0,0]
	v_pk_fma_f32 v[74:75], v[74:75], v[90:91], v[148:149] neg_lo:[1,0,0] neg_hi:[1,0,0]
	s_waitcnt lgkmcnt(0)
	v_pk_mul_f32 v[72:73], v[194:195], v[72:73]
	v_pk_mul_f32 v[74:75], v[196:197], v[74:75]
	v_cvt_pk_bf16_f32 v72, v72, v73
	v_cvt_pk_bf16_f32 v73, v74, v75
	ds_write_b64 v158, v[72:73] offset:4416
	ds_read_b64 v[72:73], v189 offset:53248
	s_waitcnt lgkmcnt(0)
	v_lshlrev_b32_e32 v148, 16, v72
	v_and_b32_e32 v149, 0xffff0000, v72
	v_lshlrev_b32_e32 v194, 16, v73
	v_and_b32_e32 v195, 0xffff0000, v73
	ds_read_b128 v[72:75], v121 offset:192
	v_pk_fma_f32 v[68:69], v[68:69], v[84:85], v[148:149] neg_lo:[1,0,0] neg_hi:[1,0,0]
	v_pk_fma_f32 v[70:71], v[70:71], v[86:87], v[194:195] neg_lo:[1,0,0] neg_hi:[1,0,0]
	v_add_u32_e32 v121, v159, v157
	v_lshl_add_u64 v[148:149], s[20:21], 1, v[116:117]
	s_waitcnt lgkmcnt(0)
	v_pk_mul_f32 v[68:69], v[72:73], v[68:69]
	v_pk_mul_f32 v[70:71], v[74:75], v[70:71]
	v_cvt_pk_bf16_f32 v68, v68, v69
	v_cvt_pk_bf16_f32 v69, v70, v71
	ds_write_b64 v158, v[68:69] offset:4448
	s_waitcnt lgkmcnt(0)
	ds_read_b128 v[68:71], v119 offset:4352
	ds_read_b128 v[72:75], v119 offset:4416
	ds_read_b128 v[194:197], v121
	ds_read_b128 v[198:201], v121 offset:64
	v_add_u32_e32 v121, v159, v180
	ds_read_b128 v[232:235], v121
	ds_read_b128 v[236:239], v121 offset:64
	ds_read_b128 v[240:243], v121 offset:2304
	ds_read_b128 v[244:247], v121 offset:2368
	ds_read_b128 v[248:251], v121 offset:4608
	s_waitcnt lgkmcnt(6)
	v_mfma_f32_16x16x32_bf16 v[194:197], v[194:197], v[68:71], 0
	s_waitcnt lgkmcnt(5)
	v_mfma_f32_16x16x32_bf16 v[194:197], v[198:201], v[72:75], v[194:197]
	ds_read_b128 v[198:201], v121 offset:4672
	v_add_u32_e32 v121, 0x1000, v158
	s_waitcnt lgkmcnt(5)
	v_mfma_f32_16x16x32_bf16 v[232:235], v[232:235], v[68:71], 0
	s_waitcnt lgkmcnt(4)
	v_mfma_f32_16x16x32_bf16 v[232:235], v[236:239], v[72:75], v[232:235]
	s_waitcnt lgkmcnt(3)
	v_mfma_f32_16x16x32_bf16 v[240:243], v[240:243], v[68:71], 0
	s_waitcnt lgkmcnt(2)
	v_mfma_f32_16x16x32_bf16 v[240:243], v[244:247], v[72:75], v[240:243]
	s_waitcnt lgkmcnt(1)
	v_mfma_f32_16x16x32_bf16 v[248:251], v[248:251], v[68:71], 0
	s_waitcnt lgkmcnt(0)
	v_mfma_f32_16x16x32_bf16 v[248:251], v[198:201], v[72:75], v[248:251]
	v_cvt_pk_bf16_f32 v72, v194, v195
	v_cvt_pk_bf16_f32 v73, v196, v197
	v_cvt_pk_bf16_f32 v74, v232, v233
	v_cvt_pk_bf16_f32 v75, v234, v235
	ds_write2_b64 v121, v[72:73], v[74:75] offset0:32 offset1:36
	v_cvt_pk_bf16_f32 v72, v240, v241
	v_cvt_pk_bf16_f32 v73, v242, v243
	s_nop 1
	v_cvt_pk_bf16_f32 v68, v248, v249
	v_cvt_pk_bf16_f32 v69, v250, v251
	ds_write2_b64 v121, v[72:73], v[68:69] offset0:40 offset1:44
	s_waitcnt lgkmcnt(0)
	s_barrier
; #define LAS __attribute__((address_space(3)))
; __device__ __forceinline__ bf16_t f2bf(float f) { return (bf16_t)(pk2(f, f) & 0xFFFFu); }
; #define MFMA16(a, b, c) __builtin_amdgcn_mfma_f32_16x16x32_bf16((a), (b), (c), 0, 0, 0)
; template <int MODE>
; __device__ NOINL void chain_item(const LAS Params* lp, int l, int item, bool ctx_out, LAS unsigned char* lds) {
;     ...
;             Bv[0] = *(const LAS bf16x8*)(RP + fr * 72 + fq * 8); Bv[1] = *(const LAS bf16x8*)(RP + fr * 72 + 32 + fq * 8);
;         } else {
;             Bv[0] = *(const LAS bf16x8*)(VT + (dvrow + fr) * 72 + ((fq ^ vkey) << 3)); Bv[1] = *(const LAS bf16x8*)(VT + (dvrow + fr) * 72 + (((4 + fq) ^ vkey) << 3));
;         }
;         {
;             typedef __attribute__((address_space(1))) bf16_t gbf16;
;             bf16_t* ob; int ldo;
;             if (MODE == 0) { if (dir == 0) { ob = p.hbuf + 256 + h * 128 + 16 * w; ldo = 1024; } else { ob = p.hyproj + h * 128 + 16 * w; ldo = 768; } }
;             else { if (dir == 0) { ob = p.hbuf + 768 + (h + hh) * 64 + 16 * (w & 3); ldo = 1024; } else { ob = p.hyproj + 512 + (h + hh) * 64 + 16 * (w & 3); ldo = 768; } }
; #pragma unroll
;             for (int ct = 0; ct < 4; ++ct) {
;                 f32x4 acc = {0.f, 0.f, 0.f, 0.f};
; #pragma unroll
;                 for (int ks = 0; ks < 2; ++ks) { const bf16x8 A = *(const LAS bf16x8*)(AT + hh * 4608 + (16 * ct + fr) * 72 + ks * 32 + fq * 8); acc = MFMA16(A, Bv[ks], acc); }
;                 gbf16* og = (gbf16*)ob + (size_t)row0 * ldo + fr;
; #pragma unroll
;                 for (int j = 0; j < 4; ++j) { const int c = 16 * ct + 4 * fq + j, tok = dir ? 63 - c : c; og[tok * ldo] = f2bf(eg[ct][j] * qs[ct][j] + acc[j]); }
;             }
;         }
;         {
;             const float gl = MODE == 0 ? gcs[128 + 63] : __expf(64.f * lg);
; #pragma unroll
;             for (int dk = 0; dk < NDK; ++dk) {
;                 Sacc[dk] = Sacc[dk] * gl;
; #pragma unroll
;                 for (int ks = 0; ks < 2; ++ks) { const bf16x8 A = *(const LAS bf16x8*)(KT + (kcol + 16 * dk + fr) * 72 + (((ks * 4 + fq) ^ (((kcol >> 4) + dk) & 7)) << 3)); Sacc[dk] = MFMA16(A, Bv[ks], Sacc[dk]); }
	ds_read_b128 v[72:75], v119 offset:4352
	ds_read_b128 v[68:71], v119 offset:4416
	v_add_u32_e32 v218, v160, v157
	v_add_u32_e32 v219, v160, v180
	v_mov_b32_e32 v119, v1
	v_mov_b32_e32 v121, v1
	ds_read_b128 v[194:197], v218
	ds_read_b128 v[232:235], v219
	ds_read_b128 v[244:247], v219 offset:2304
	ds_read_b128 v[236:239], v219 offset:4608
	ds_read_b128 v[198:201], v218 offset:64
	ds_read_b128 v[240:243], v219 offset:64
	ds_read_b128 v[248:251], v219 offset:2368
	s_waitcnt lgkmcnt(6)
	v_mfma_f32_16x16x32_bf16 v[194:197], v[194:197], v[72:75], 0
	s_waitcnt lgkmcnt(5)
	v_mfma_f32_16x16x32_bf16 v[232:235], v[232:235], v[72:75], 0
	s_waitcnt lgkmcnt(4)
	v_mfma_f32_16x16x32_bf16 v[244:247], v[244:247], v[72:75], 0
	s_waitcnt lgkmcnt(3)
	v_mfma_f32_16x16x32_bf16 v[236:239], v[236:239], v[72:75], 0
	s_waitcnt lgkmcnt(2)
	v_mfma_f32_16x16x32_bf16 v[194:197], v[198:201], v[68:71], v[194:197]
	ds_read_b128 v[198:201], v219 offset:4672
	s_waitcnt lgkmcnt(2)
	v_mfma_f32_16x16x32_bf16 v[232:235], v[240:243], v[68:71], v[232:235]
	s_waitcnt lgkmcnt(1)
	v_mfma_f32_16x16x32_bf16 v[244:247], v[248:251], v[68:71], v[244:247]
	s_waitcnt lgkmcnt(0)
	v_mfma_f32_16x16x32_bf16 v[236:239], v[198:201], v[68:71], v[236:239]
	v_lshl_add_u64 v[240:241], v[148:149], 0, v[0:1]
	v_lshl_add_u64 v[242:243], v[148:149], 0, v[118:119]
	v_lshl_add_u64 v[248:249], v[148:149], 0, v[120:121]
	v_lshl_add_u64 v[250:251], v[148:149], 0, v[122:123]
	s_nop 3
	v_fma_f32 v194, v96, v104, v194
	v_fma_f32 v195, v97, v105, v195
	v_fma_f32 v196, v98, v106, v196
	v_fma_f32 v197, v99, v107, v197
	v_cvt_pk_bf16_f32 v194, v194, v194
	v_cvt_pk_bf16_f32 v195, v195, v195
	v_cvt_pk_bf16_f32 v196, v196, v196
	v_cvt_pk_bf16_f32 v197, v197, v197
	global_store_short v[240:241], v194, off
	global_store_short v[242:243], v195, off
	global_store_short v[248:249], v196, off
	global_store_short v[250:251], v197, off
	v_lshl_add_u64 v[240:241], v[148:149], 0, v[124:125]
	v_lshl_add_u64 v[242:243], v[148:149], 0, v[126:127]
	v_lshl_add_u64 v[248:249], v[148:149], 0, v[128:129]
	v_lshl_add_u64 v[250:251], v[148:149], 0, v[130:131]
	v_fma_f32 v232, v92, v100, v232
	v_fma_f32 v233, v93, v101, v233
	v_fma_f32 v234, v94, v102, v234
	v_fma_f32 v235, v95, v103, v235
	v_cvt_pk_bf16_f32 v232, v232, v232
	v_cvt_pk_bf16_f32 v233, v233, v233
	v_cvt_pk_bf16_f32 v234, v234, v234
	v_cvt_pk_bf16_f32 v235, v235, v235
	global_store_short v[240:241], v232, off
	global_store_short v[242:243], v233, off
	global_store_short v[248:249], v234, off
	global_store_short v[250:251], v235, off
	v_lshl_add_u64 v[240:241], v[148:149], 0, v[132:133]
	v_lshl_add_u64 v[242:243], v[148:149], 0, v[134:135]
	v_lshl_add_u64 v[248:249], v[148:149], 0, v[136:137]
	v_lshl_add_u64 v[250:251], v[148:149], 0, v[138:139]
	v_fma_f32 v244, v80, v88, v244
	v_fma_f32 v245, v81, v89, v245
	v_fma_f32 v246, v82, v90, v246
	v_fma_f32 v247, v83, v91, v247
	v_cvt_pk_bf16_f32 v244, v244, v244
	v_cvt_pk_bf16_f32 v245, v245, v245
	v_cvt_pk_bf16_f32 v246, v246, v246
	v_cvt_pk_bf16_f32 v247, v247, v247
	global_store_short v[240:241], v244, off
	global_store_short v[242:243], v245, off
	global_store_short v[248:249], v246, off
	global_store_short v[250:251], v247, off
	v_lshl_add_u64 v[240:241], v[148:149], 0, v[140:141]
	v_lshl_add_u64 v[242:243], v[148:149], 0, v[142:143]
	v_lshl_add_u64 v[248:249], v[148:149], 0, v[144:145]
	v_lshl_add_u64 v[250:251], v[148:149], 0, v[146:147]
	v_fma_f32 v236, v76, v84, v236
	v_fma_f32 v237, v77, v85, v237
	v_fma_f32 v238, v78, v86, v238
	v_fma_f32 v239, v79, v87, v239
	v_cvt_pk_bf16_f32 v236, v236, v236
	v_cvt_pk_bf16_f32 v237, v237, v237
	v_cvt_pk_bf16_f32 v238, v238, v238
	v_cvt_pk_bf16_f32 v239, v239, v239
	global_store_short v[240:241], v236, off
	global_store_short v[242:243], v237, off
	global_store_short v[248:249], v238, off
	global_store_short v[250:251], v239, off
	v_mov_b32_e32 v76, s17
	ds_read_b32 v76, v76
	v_add_u32_e32 v83, v161, v155
	v_add_u32_e32 v82, v181, v182
	v_add_u32_e32 v84, v161, v182
	v_add_u32_e32 v85, v161, v183
	v_add_u32_e32 v86, v161, v162
	ds_read_b128 v[88:91], v83 offset:34816
	ds_read_b128 v[92:95], v82 offset:34816
	ds_read_b128 v[96:99], v190 offset:34816
	ds_read_b128 v[100:103], v191 offset:34816
	ds_read_b128 v[104:107], v83 offset:44096
	ds_read_b128 v[194:197], v84 offset:46400
	ds_read_b128 v[198:201], v85 offset:48704
	ds_read_b128 v[232:235], v86 offset:51008
	s_waitcnt lgkmcnt(8)
; #define LAS __attribute__((address_space(3)))
; #define MFMA16(a, b, c) __builtin_amdgcn_mfma_f32_16x16x32_bf16((a), (b), (c), 0, 0, 0)
; template <int MODE>
; __device__ NOINL void chain_item(const LAS Params* lp, int l, int item, bool ctx_out, LAS unsigned char* lds) {
;     ...
;         {
;             const float gl = MODE == 0 ? gcs[128 + 63] : __expf(64.f * lg);
; #pragma unroll
;             for (int dk = 0; dk < NDK; ++dk) {
;                 Sacc[dk] = Sacc[dk] * gl;
; #pragma unroll
;                 for (int ks = 0; ks < 2; ++ks) { const bf16x8 A = *(const LAS bf16x8*)(KT + (kcol + 16 * dk + fr) * 72 + (((ks * 4 + fq) ^ (((kcol >> 4) + dk) & 7)) << 3)); Sacc[dk] = MFMA16(A, Bv[ks], Sacc[dk]); }
;             }
	v_mul_f32_e32 v30, v30, v76
	v_mul_f32_e32 v31, v31, v76
	v_mul_f32_e32 v28, v28, v76
	v_mul_f32_e32 v29, v29, v76
	v_mul_f32_e32 v42, v42, v76
	v_mul_f32_e32 v43, v43, v76
	v_mul_f32_e32 v40, v40, v76
	v_mul_f32_e32 v41, v41, v76
	v_mul_f32_e32 v34, v34, v76
	v_mul_f32_e32 v35, v35, v76
	v_mul_f32_e32 v32, v32, v76
	v_mul_f32_e32 v33, v33, v76
	v_mul_f32_e32 v38, v38, v76
	v_mul_f32_e32 v39, v39, v76
	v_mul_f32_e32 v36, v36, v76
	v_mul_f32_e32 v37, v37, v76
	v_mul_f32_e32 v58, v58, v76
	v_mul_f32_e32 v59, v59, v76
	v_mul_f32_e32 v56, v56, v76
	v_mul_f32_e32 v57, v57, v76
	v_mul_f32_e32 v54, v54, v76
	v_mul_f32_e32 v55, v55, v76
	v_mul_f32_e32 v52, v52, v76
	v_mul_f32_e32 v53, v53, v76
	v_mul_f32_e32 v46, v46, v76
	v_mul_f32_e32 v47, v47, v76
	v_mul_f32_e32 v44, v44, v76
	v_mul_f32_e32 v45, v45, v76
	v_mul_f32_e32 v50, v50, v76
	v_mul_f32_e32 v51, v51, v76
	v_mul_f32_e32 v48, v48, v76
	v_mul_f32_e32 v49, v49, v76
	s_waitcnt lgkmcnt(7)
	v_mfma_f32_16x16x32_bf16 v[28:31], v[88:91], v[72:75], v[28:31]
	ds_read_b128 v[88:91], v83 offset:34880
	s_waitcnt lgkmcnt(7)
	v_mfma_f32_16x16x32_bf16 v[40:43], v[92:95], v[72:75], v[40:43]
	ds_read_b128 v[92:95], v82 offset:34880
	s_waitcnt lgkmcnt(7)
	v_mfma_f32_16x16x32_bf16 v[32:35], v[96:99], v[72:75], v[32:35]
	ds_read_b128 v[96:99], v190 offset:34880
	s_waitcnt lgkmcnt(7)
	v_mfma_f32_16x16x32_bf16 v[36:39], v[100:103], v[72:75], v[36:39]
	ds_read_b128 v[100:103], v191 offset:34880
	s_waitcnt lgkmcnt(7)
	v_mfma_f32_16x16x32_bf16 v[56:59], v[104:107], v[72:75], v[56:59]
	ds_read_b128 v[104:107], v83 offset:44032
	s_waitcnt lgkmcnt(7)
	v_mfma_f32_16x16x32_bf16 v[52:55], v[194:197], v[72:75], v[52:55]
	ds_read_b128 v[194:197], v84 offset:46336
	s_waitcnt lgkmcnt(7)
	v_mfma_f32_16x16x32_bf16 v[44:47], v[198:201], v[72:75], v[44:47]
	ds_read_b128 v[198:201], v85 offset:48640
	s_waitcnt lgkmcnt(7)
	v_mfma_f32_16x16x32_bf16 v[48:51], v[232:235], v[72:75], v[48:51]
	ds_read_b128 v[232:235], v86 offset:50944
	s_waitcnt lgkmcnt(7)
	v_mfma_f32_16x16x32_bf16 v[28:31], v[88:91], v[68:71], v[28:31]
	s_waitcnt lgkmcnt(6)
	v_mfma_f32_16x16x32_bf16 v[40:43], v[92:95], v[68:71], v[40:43]
	s_waitcnt lgkmcnt(5)
	v_mfma_f32_16x16x32_bf16 v[32:35], v[96:99], v[68:71], v[32:35]
	s_waitcnt lgkmcnt(4)
	v_mfma_f32_16x16x32_bf16 v[36:39], v[100:103], v[68:71], v[36:39]
	s_waitcnt lgkmcnt(3)
	v_mfma_f32_16x16x32_bf16 v[56:59], v[104:107], v[68:71], v[56:59]
	s_waitcnt lgkmcnt(2)
	v_mfma_f32_16x16x32_bf16 v[52:55], v[194:197], v[68:71], v[52:55]
	s_waitcnt lgkmcnt(1)
	v_mfma_f32_16x16x32_bf16 v[44:47], v[198:201], v[68:71], v[44:47]
	s_waitcnt lgkmcnt(0)
	v_mfma_f32_16x16x32_bf16 v[48:51], v[232:235], v[68:71], v[48:51]
	s_waitcnt vmcnt(19)
	v_mov_b64_e32 v[74:75], v[66:67]
	v_mov_b64_e32 v[70:71], v[62:63]
	v_mov_b64_e32 v[72:73], v[64:65]
	v_mov_b64_e32 v[68:69], v[60:61]
	s_cbranch_scc0 .LBB0_1135
